# v29 + hand-written SwiGLU epilogue for the gate/up GEMM: 473 instead of 614 instructions per tile (re-associated f32 math, interleaved transcendental chains, one 64-bit add per row group)
# baseline (speedup 1.0000x reference)
.LBB0_1801:
	s_waitcnt vmcnt(0)
	v_lshl_add_u32 v186, s9, 8, v1
	v_lshl_or_b32 v184, s8, 7, v143
	v_readlane_b32 s8, v245, 21
	v_readlane_b32 s9, v245, 22
	v_ashrrev_i32_e32 v185, 31, v184
	s_movk_i32 s5, 0x2c00
	v_lshlrev_b64 v[184:185], 1, v[184:185]
	s_mov_b32 s101, 0
	v_mov_b64_e32 v[182:183], s[8:9]
	s_mov_b32 s100, 0x2c000
	v_mad_i64_i32 v[180:181], vcc, v186, s5, v[182:183]
	s_mov_b64 s[22:23], -1
	v_lshl_add_u64 v[180:181], v[180:181], 0, v[184:185]
	s_mov_b32 s26, 0x2aaaaaab
	v_mul_f32_e32 v182, 0xbfb8aa3b, v158
	v_mul_f32_e32 v183, v158, v158
	v_mul_f32_e32 v118, v126, v118
	v_rcp_f32_e32 v183, v183
	v_mul_f32_e32 v119, v127, v119
	v_mul_f32_e32 v120, v128, v120
	v_mul_f32_e32 v121, v129, v121
	v_mul_f32_e32 v114, v122, v114
	v_mul_f32_e32 v115, v123, v115
	v_mul_f32_e32 v116, v124, v116
	v_mul_f32_e32 v117, v125, v117
	v_mul_f32_e32 v126, v182, v126
	v_mul_f32_e32 v127, v182, v127
	v_mul_f32_e32 v128, v182, v128
	v_mul_f32_e32 v129, v182, v129
	v_mul_f32_e32 v122, v182, v122
	v_mul_f32_e32 v123, v182, v123
	v_mul_f32_e32 v124, v182, v124
	v_mul_f32_e32 v125, v182, v125
	v_exp_f32_e32 v126, v126
	v_exp_f32_e32 v127, v127
	v_exp_f32_e32 v128, v128
	v_exp_f32_e32 v129, v129
	v_exp_f32_e32 v122, v122
	v_exp_f32_e32 v123, v123
	v_exp_f32_e32 v124, v124
	v_exp_f32_e32 v125, v125
	v_fma_f32 v126, v126, v183, v183
	v_fma_f32 v127, v127, v183, v183
	v_fma_f32 v128, v128, v183, v183
	v_fma_f32 v129, v129, v183, v183
	v_fma_f32 v122, v122, v183, v183
	v_fma_f32 v123, v123, v183, v183
	v_fma_f32 v124, v124, v183, v183
	v_fma_f32 v125, v125, v183, v183
	v_rcp_f32_e32 v126, v126
	v_rcp_f32_e32 v127, v127
	v_rcp_f32_e32 v128, v128
	v_rcp_f32_e32 v129, v129
	v_rcp_f32_e32 v122, v122
	v_rcp_f32_e32 v123, v123
	v_rcp_f32_e32 v124, v124
	v_rcp_f32_e32 v125, v125
	v_mul_f32_e32 v118, v118, v126
	v_mul_f32_e32 v119, v119, v127
	v_mul_f32_e32 v120, v120, v128
	v_mul_f32_e32 v121, v121, v129
	v_mul_f32_e32 v114, v114, v122
	v_mul_f32_e32 v115, v115, v123
	v_mul_f32_e32 v116, v116, v124
	v_mul_f32_e32 v117, v117, v125
	v_cvt_pk_bf16_f32 v126, v118, v119
	v_cvt_pk_bf16_f32 v127, v120, v121
	v_cvt_pk_bf16_f32 v128, v114, v115
	v_cvt_pk_bf16_f32 v129, v116, v117
	global_store_dwordx4 v[180:181], v[126:129], off
	v_lshl_add_u64 v[180:181], v[180:181], 0, s[100:101]
	v_mul_f32_e32 v182, 0xbfb8aa3b, v156
	v_mul_f32_e32 v183, v156, v156
	v_mul_f32_e32 v102, v110, v102
	v_rcp_f32_e32 v183, v183
	v_mul_f32_e32 v103, v111, v103
	v_mul_f32_e32 v104, v112, v104
	v_mul_f32_e32 v105, v113, v105
	v_mul_f32_e32 v98, v106, v98
	v_mul_f32_e32 v99, v107, v99
	v_mul_f32_e32 v100, v108, v100
	v_mul_f32_e32 v101, v109, v101
	v_mul_f32_e32 v110, v182, v110
	v_mul_f32_e32 v111, v182, v111
	v_mul_f32_e32 v112, v182, v112
	v_mul_f32_e32 v113, v182, v113
	v_mul_f32_e32 v106, v182, v106
	v_mul_f32_e32 v107, v182, v107
	v_mul_f32_e32 v108, v182, v108
	v_mul_f32_e32 v109, v182, v109
	v_exp_f32_e32 v110, v110
	v_exp_f32_e32 v111, v111
	v_exp_f32_e32 v112, v112
	v_exp_f32_e32 v113, v113
	v_exp_f32_e32 v106, v106
	v_exp_f32_e32 v107, v107
	v_exp_f32_e32 v108, v108
	v_exp_f32_e32 v109, v109
	v_fma_f32 v110, v110, v183, v183
	v_fma_f32 v111, v111, v183, v183
	v_fma_f32 v112, v112, v183, v183
	v_fma_f32 v113, v113, v183, v183
	v_fma_f32 v106, v106, v183, v183
	v_fma_f32 v107, v107, v183, v183
	v_fma_f32 v108, v108, v183, v183
	v_fma_f32 v109, v109, v183, v183
	v_rcp_f32_e32 v110, v110
	v_rcp_f32_e32 v111, v111
	v_rcp_f32_e32 v112, v112
	v_rcp_f32_e32 v113, v113
	v_rcp_f32_e32 v106, v106
	v_rcp_f32_e32 v107, v107
	v_rcp_f32_e32 v108, v108
	v_rcp_f32_e32 v109, v109
	v_mul_f32_e32 v102, v102, v110
	v_mul_f32_e32 v103, v103, v111
	v_mul_f32_e32 v104, v104, v112
	v_mul_f32_e32 v105, v105, v113
	v_mul_f32_e32 v98, v98, v106
	v_mul_f32_e32 v99, v99, v107
	v_mul_f32_e32 v100, v100, v108
	v_mul_f32_e32 v101, v101, v109
	v_cvt_pk_bf16_f32 v110, v102, v103
	v_cvt_pk_bf16_f32 v111, v104, v105
	v_cvt_pk_bf16_f32 v112, v98, v99
	v_cvt_pk_bf16_f32 v113, v100, v101
	global_store_dwordx4 v[180:181], v[110:113], off
	v_lshl_add_u64 v[180:181], v[180:181], 0, s[100:101]
	v_mul_f32_e32 v182, 0xbfb8aa3b, v150
	v_mul_f32_e32 v183, v150, v150
	v_mul_f32_e32 v86, v94, v86
	v_rcp_f32_e32 v183, v183
	v_mul_f32_e32 v87, v95, v87
	v_mul_f32_e32 v88, v96, v88
	v_mul_f32_e32 v89, v97, v89
	v_mul_f32_e32 v82, v90, v82
	v_mul_f32_e32 v83, v91, v83
	v_mul_f32_e32 v84, v92, v84
	v_mul_f32_e32 v85, v93, v85
	v_mul_f32_e32 v94, v182, v94
	v_mul_f32_e32 v95, v182, v95
	v_mul_f32_e32 v96, v182, v96
	v_mul_f32_e32 v97, v182, v97
	v_mul_f32_e32 v90, v182, v90
	v_mul_f32_e32 v91, v182, v91
	v_mul_f32_e32 v92, v182, v92
	v_mul_f32_e32 v93, v182, v93
	v_exp_f32_e32 v94, v94
	v_exp_f32_e32 v95, v95
	v_exp_f32_e32 v96, v96
	v_exp_f32_e32 v97, v97
	v_exp_f32_e32 v90, v90
	v_exp_f32_e32 v91, v91
	v_exp_f32_e32 v92, v92
	v_exp_f32_e32 v93, v93
	v_fma_f32 v94, v94, v183, v183
	v_fma_f32 v95, v95, v183, v183
	v_fma_f32 v96, v96, v183, v183
	v_fma_f32 v97, v97, v183, v183
	v_fma_f32 v90, v90, v183, v183
	v_fma_f32 v91, v91, v183, v183
	v_fma_f32 v92, v92, v183, v183
	v_fma_f32 v93, v93, v183, v183
	v_rcp_f32_e32 v94, v94
	v_rcp_f32_e32 v95, v95
	v_rcp_f32_e32 v96, v96
	v_rcp_f32_e32 v97, v97
	v_rcp_f32_e32 v90, v90
	v_rcp_f32_e32 v91, v91
	v_rcp_f32_e32 v92, v92
	v_rcp_f32_e32 v93, v93
	v_mul_f32_e32 v86, v86, v94
	v_mul_f32_e32 v87, v87, v95
	v_mul_f32_e32 v88, v88, v96
	v_mul_f32_e32 v89, v89, v97
	v_mul_f32_e32 v82, v82, v90
	v_mul_f32_e32 v83, v83, v91
	v_mul_f32_e32 v84, v84, v92
	v_mul_f32_e32 v85, v85, v93
	v_cvt_pk_bf16_f32 v94, v86, v87
	v_cvt_pk_bf16_f32 v95, v88, v89
	v_cvt_pk_bf16_f32 v96, v82, v83
	v_cvt_pk_bf16_f32 v97, v84, v85
	global_store_dwordx4 v[180:181], v[94:97], off
	v_lshl_add_u64 v[180:181], v[180:181], 0, s[100:101]
	v_mul_f32_e32 v182, 0xbfb8aa3b, v148
	v_mul_f32_e32 v183, v148, v148
	v_mul_f32_e32 v70, v78, v70
	v_rcp_f32_e32 v183, v183
	v_mul_f32_e32 v71, v79, v71
	v_mul_f32_e32 v72, v80, v72
	v_mul_f32_e32 v73, v81, v73
	v_mul_f32_e32 v66, v74, v66
	v_mul_f32_e32 v67, v75, v67
	v_mul_f32_e32 v68, v76, v68
	v_mul_f32_e32 v69, v77, v69
	v_mul_f32_e32 v78, v182, v78
	v_mul_f32_e32 v79, v182, v79
	v_mul_f32_e32 v80, v182, v80
	v_mul_f32_e32 v81, v182, v81
	v_mul_f32_e32 v74, v182, v74
	v_mul_f32_e32 v75, v182, v75
	v_mul_f32_e32 v76, v182, v76
	v_mul_f32_e32 v77, v182, v77
	v_exp_f32_e32 v78, v78
	v_exp_f32_e32 v79, v79
	v_exp_f32_e32 v80, v80
	v_exp_f32_e32 v81, v81
	v_exp_f32_e32 v74, v74
	v_exp_f32_e32 v75, v75
	v_exp_f32_e32 v76, v76
	v_exp_f32_e32 v77, v77
	v_fma_f32 v78, v78, v183, v183
	v_fma_f32 v79, v79, v183, v183
	v_fma_f32 v80, v80, v183, v183
	v_fma_f32 v81, v81, v183, v183
	v_fma_f32 v74, v74, v183, v183
	v_fma_f32 v75, v75, v183, v183
	v_fma_f32 v76, v76, v183, v183
	v_fma_f32 v77, v77, v183, v183
	v_rcp_f32_e32 v78, v78
	v_rcp_f32_e32 v79, v79
	v_rcp_f32_e32 v80, v80
	v_rcp_f32_e32 v81, v81
	v_rcp_f32_e32 v74, v74
	v_rcp_f32_e32 v75, v75
	v_rcp_f32_e32 v76, v76
	v_rcp_f32_e32 v77, v77
	v_mul_f32_e32 v70, v70, v78
	v_mul_f32_e32 v71, v71, v79
	v_mul_f32_e32 v72, v72, v80
	v_mul_f32_e32 v73, v73, v81
	v_mul_f32_e32 v66, v66, v74
	v_mul_f32_e32 v67, v67, v75
	v_mul_f32_e32 v68, v68, v76
	v_mul_f32_e32 v69, v69, v77
	v_cvt_pk_bf16_f32 v78, v70, v71
	v_cvt_pk_bf16_f32 v79, v72, v73
	v_cvt_pk_bf16_f32 v80, v66, v67
	v_cvt_pk_bf16_f32 v81, v68, v69
	global_store_dwordx4 v[180:181], v[78:81], off
	s_mov_b32 s100, 0xdc000
	v_lshl_add_u64 v[180:181], v[180:181], 0, s[100:101]
	s_mov_b32 s100, 0x2c000
	v_mul_f32_e32 v182, 0xbfb8aa3b, v146
	v_mul_f32_e32 v183, v146, v146
	v_mul_f32_e32 v54, v62, v54
	v_rcp_f32_e32 v183, v183
	v_mul_f32_e32 v55, v63, v55
	v_mul_f32_e32 v56, v64, v56
	v_mul_f32_e32 v57, v65, v57
	v_mul_f32_e32 v50, v58, v50
	v_mul_f32_e32 v51, v59, v51
	v_mul_f32_e32 v52, v60, v52
	v_mul_f32_e32 v53, v61, v53
	v_mul_f32_e32 v62, v182, v62
	v_mul_f32_e32 v63, v182, v63
	v_mul_f32_e32 v64, v182, v64
	v_mul_f32_e32 v65, v182, v65
	v_mul_f32_e32 v58, v182, v58
	v_mul_f32_e32 v59, v182, v59
	v_mul_f32_e32 v60, v182, v60
	v_mul_f32_e32 v61, v182, v61
	v_exp_f32_e32 v62, v62
	v_exp_f32_e32 v63, v63
	v_exp_f32_e32 v64, v64
	v_exp_f32_e32 v65, v65
	v_exp_f32_e32 v58, v58
	v_exp_f32_e32 v59, v59
	v_exp_f32_e32 v60, v60
	v_exp_f32_e32 v61, v61
	v_fma_f32 v62, v62, v183, v183
	v_fma_f32 v63, v63, v183, v183
	v_fma_f32 v64, v64, v183, v183
	v_fma_f32 v65, v65, v183, v183
	v_fma_f32 v58, v58, v183, v183
	v_fma_f32 v59, v59, v183, v183
	v_fma_f32 v60, v60, v183, v183
	v_fma_f32 v61, v61, v183, v183
	v_rcp_f32_e32 v62, v62
	v_rcp_f32_e32 v63, v63
	v_rcp_f32_e32 v64, v64
	v_rcp_f32_e32 v65, v65
	v_rcp_f32_e32 v58, v58
	v_rcp_f32_e32 v59, v59
	v_rcp_f32_e32 v60, v60
	v_rcp_f32_e32 v61, v61
	v_mul_f32_e32 v54, v54, v62
	v_mul_f32_e32 v55, v55, v63
	v_mul_f32_e32 v56, v56, v64
	v_mul_f32_e32 v57, v57, v65
	v_mul_f32_e32 v50, v50, v58
	v_mul_f32_e32 v51, v51, v59
	v_mul_f32_e32 v52, v52, v60
	v_mul_f32_e32 v53, v53, v61
	v_cvt_pk_bf16_f32 v62, v54, v55
	v_cvt_pk_bf16_f32 v63, v56, v57
	v_cvt_pk_bf16_f32 v64, v50, v51
	v_cvt_pk_bf16_f32 v65, v52, v53
	global_store_dwordx4 v[180:181], v[62:65], off
	v_lshl_add_u64 v[180:181], v[180:181], 0, s[100:101]
	v_mul_f32_e32 v182, 0xbfb8aa3b, v144
	v_mul_f32_e32 v183, v144, v144
	v_mul_f32_e32 v38, v46, v38
	v_rcp_f32_e32 v183, v183
	v_mul_f32_e32 v39, v47, v39
	v_mul_f32_e32 v40, v48, v40
	v_mul_f32_e32 v41, v49, v41
	v_mul_f32_e32 v34, v42, v34
	v_mul_f32_e32 v35, v43, v35
	v_mul_f32_e32 v36, v44, v36
	v_mul_f32_e32 v37, v45, v37
	v_mul_f32_e32 v46, v182, v46
	v_mul_f32_e32 v47, v182, v47
	v_mul_f32_e32 v48, v182, v48
	v_mul_f32_e32 v49, v182, v49
	v_mul_f32_e32 v42, v182, v42
	v_mul_f32_e32 v43, v182, v43
	v_mul_f32_e32 v44, v182, v44
	v_mul_f32_e32 v45, v182, v45
	v_exp_f32_e32 v46, v46
	v_exp_f32_e32 v47, v47
	v_exp_f32_e32 v48, v48
	v_exp_f32_e32 v49, v49
	v_exp_f32_e32 v42, v42
	v_exp_f32_e32 v43, v43
	v_exp_f32_e32 v44, v44
	v_exp_f32_e32 v45, v45
	v_fma_f32 v46, v46, v183, v183
	v_fma_f32 v47, v47, v183, v183
	v_fma_f32 v48, v48, v183, v183
	v_fma_f32 v49, v49, v183, v183
	v_fma_f32 v42, v42, v183, v183
	v_fma_f32 v43, v43, v183, v183
	v_fma_f32 v44, v44, v183, v183
	v_fma_f32 v45, v45, v183, v183
	v_rcp_f32_e32 v46, v46
	v_rcp_f32_e32 v47, v47
	v_rcp_f32_e32 v48, v48
	v_rcp_f32_e32 v49, v49
	v_rcp_f32_e32 v42, v42
	v_rcp_f32_e32 v43, v43
	v_rcp_f32_e32 v44, v44
	v_rcp_f32_e32 v45, v45
	v_mul_f32_e32 v38, v38, v46
	v_mul_f32_e32 v39, v39, v47
	v_mul_f32_e32 v40, v40, v48
	v_mul_f32_e32 v41, v41, v49
	v_mul_f32_e32 v34, v34, v42
	v_mul_f32_e32 v35, v35, v43
	v_mul_f32_e32 v36, v36, v44
	v_mul_f32_e32 v37, v37, v45
	v_cvt_pk_bf16_f32 v46, v38, v39
	v_cvt_pk_bf16_f32 v47, v40, v41
	v_cvt_pk_bf16_f32 v48, v34, v35
	v_cvt_pk_bf16_f32 v49, v36, v37
	global_store_dwordx4 v[180:181], v[46:49], off
	v_lshl_add_u64 v[180:181], v[180:181], 0, s[100:101]
	v_mul_f32_e32 v182, 0xbfb8aa3b, v142
	v_mul_f32_e32 v183, v142, v142
	v_mul_f32_e32 v22, v30, v22
	v_rcp_f32_e32 v183, v183
	v_mul_f32_e32 v23, v31, v23
	v_mul_f32_e32 v24, v32, v24
	v_mul_f32_e32 v25, v33, v25
	v_mul_f32_e32 v18, v26, v18
	v_mul_f32_e32 v19, v27, v19
	v_mul_f32_e32 v20, v28, v20
	v_mul_f32_e32 v21, v29, v21
	v_mul_f32_e32 v30, v182, v30
	v_mul_f32_e32 v31, v182, v31
	v_mul_f32_e32 v32, v182, v32
	v_mul_f32_e32 v33, v182, v33
	v_mul_f32_e32 v26, v182, v26
	v_mul_f32_e32 v27, v182, v27
	v_mul_f32_e32 v28, v182, v28
	v_mul_f32_e32 v29, v182, v29
	v_exp_f32_e32 v30, v30
	v_exp_f32_e32 v31, v31
	v_exp_f32_e32 v32, v32
	v_exp_f32_e32 v33, v33
	v_exp_f32_e32 v26, v26
	v_exp_f32_e32 v27, v27
	v_exp_f32_e32 v28, v28
	v_exp_f32_e32 v29, v29
	v_fma_f32 v30, v30, v183, v183
	v_fma_f32 v31, v31, v183, v183
	v_fma_f32 v32, v32, v183, v183
	v_fma_f32 v33, v33, v183, v183
	v_fma_f32 v26, v26, v183, v183
	v_fma_f32 v27, v27, v183, v183
	v_fma_f32 v28, v28, v183, v183
	v_fma_f32 v29, v29, v183, v183
	v_rcp_f32_e32 v30, v30
	v_rcp_f32_e32 v31, v31
	v_rcp_f32_e32 v32, v32
	v_rcp_f32_e32 v33, v33
	v_rcp_f32_e32 v26, v26
	v_rcp_f32_e32 v27, v27
	v_rcp_f32_e32 v28, v28
	v_rcp_f32_e32 v29, v29
	v_mul_f32_e32 v22, v22, v30
	v_mul_f32_e32 v23, v23, v31
	v_mul_f32_e32 v24, v24, v32
	v_mul_f32_e32 v25, v25, v33
	v_mul_f32_e32 v18, v18, v26
	v_mul_f32_e32 v19, v19, v27
	v_mul_f32_e32 v20, v20, v28
	v_mul_f32_e32 v21, v21, v29
	v_cvt_pk_bf16_f32 v30, v22, v23
	v_cvt_pk_bf16_f32 v31, v24, v25
	v_cvt_pk_bf16_f32 v32, v18, v19
	v_cvt_pk_bf16_f32 v33, v20, v21
	global_store_dwordx4 v[180:181], v[30:33], off
	v_lshl_add_u64 v[180:181], v[180:181], 0, s[100:101]
	v_mul_f32_e32 v182, 0xbfb8aa3b, v140
	v_mul_f32_e32 v183, v140, v140
	v_mul_f32_e32 v6, v14, v6
	v_rcp_f32_e32 v183, v183
	v_mul_f32_e32 v7, v15, v7
	v_mul_f32_e32 v8, v16, v8
	v_mul_f32_e32 v9, v17, v9
	v_mul_f32_e32 v2, v10, v2
	v_mul_f32_e32 v3, v11, v3
	v_mul_f32_e32 v4, v12, v4
	v_mul_f32_e32 v5, v13, v5
	v_mul_f32_e32 v14, v182, v14
	v_mul_f32_e32 v15, v182, v15
	v_mul_f32_e32 v16, v182, v16
	v_mul_f32_e32 v17, v182, v17
	v_mul_f32_e32 v10, v182, v10
	v_mul_f32_e32 v11, v182, v11
	v_mul_f32_e32 v12, v182, v12
	v_mul_f32_e32 v13, v182, v13
	v_exp_f32_e32 v14, v14
	v_exp_f32_e32 v15, v15
	v_exp_f32_e32 v16, v16
	v_exp_f32_e32 v17, v17
	v_exp_f32_e32 v10, v10
	v_exp_f32_e32 v11, v11
	v_exp_f32_e32 v12, v12
	v_exp_f32_e32 v13, v13
	v_fma_f32 v14, v14, v183, v183
	v_fma_f32 v15, v15, v183, v183
	v_fma_f32 v16, v16, v183, v183
	v_fma_f32 v17, v17, v183, v183
	v_fma_f32 v10, v10, v183, v183
	v_fma_f32 v11, v11, v183, v183
	v_fma_f32 v12, v12, v183, v183
	v_fma_f32 v13, v13, v183, v183
	v_rcp_f32_e32 v14, v14
	v_rcp_f32_e32 v15, v15
	v_rcp_f32_e32 v16, v16
	v_rcp_f32_e32 v17, v17
	v_rcp_f32_e32 v10, v10
	v_rcp_f32_e32 v11, v11
	v_rcp_f32_e32 v12, v12
	v_rcp_f32_e32 v13, v13
	v_mul_f32_e32 v6, v6, v14
	v_mul_f32_e32 v7, v7, v15
	v_mul_f32_e32 v8, v8, v16
	v_mul_f32_e32 v9, v9, v17
	v_mul_f32_e32 v2, v2, v10
	v_mul_f32_e32 v3, v3, v11
	v_mul_f32_e32 v4, v4, v12
	v_mul_f32_e32 v5, v5, v13
	v_cvt_pk_bf16_f32 v14, v6, v7
	v_cvt_pk_bf16_f32 v15, v8, v9
	v_cvt_pk_bf16_f32 v16, v2, v3
	v_cvt_pk_bf16_f32 v17, v4, v5
	global_store_dwordx4 v[180:181], v[14:17], off
	s_andn2_b64 vcc, exec, s[34:35]
	s_cbranch_vccnz .LBB0_1794
	s_nop 0
	v_lshl_add_u32 v2, s18, 8, v1
	v_readlane_b32 s8, v245, 16
	v_ashrrev_i32_e32 v3, 31, v2
	v_readlane_b32 s9, v245, 17
	s_andn2_b64 vcc, exec, s[0:1]
	s_nop 0
	v_lshl_add_u64 v[2:3], v[2:3], 2, s[8:9]
	global_load_dword v158, v[2:3], off
	global_load_dword v156, v[2:3], off offset:64
	global_load_dword v150, v[2:3], off offset:128
	global_load_dword v148, v[2:3], off offset:192
	global_load_dword v146, v[2:3], off offset:512
	global_load_dword v144, v[2:3], off offset:576
	global_load_dword v142, v[2:3], off offset:640
	global_load_dword v140, v[2:3], off offset:704
	s_cbranch_vccnz .LBB0_1793
	s_barrier
	s_branch .LBB0_1793

	.amdhsa_kernel _Z9trunk_fwd4Args
		.amdhsa_group_segment_fixed_size 0
		.amdhsa_private_segment_fixed_size 0
		.amdhsa_kernarg_size 496
		.amdhsa_user_sgpr_count 2
		.amdhsa_user_sgpr_dispatch_ptr 0
		.amdhsa_user_sgpr_queue_ptr 0
		.amdhsa_user_sgpr_kernarg_segment_ptr 1
		.amdhsa_user_sgpr_dispatch_id 0
		.amdhsa_user_sgpr_kernarg_preload_length 0
		.amdhsa_user_sgpr_kernarg_preload_offset 0
		.amdhsa_user_sgpr_private_segment_size 0
		.amdhsa_uses_dynamic_stack 0
		.amdhsa_enable_private_segment 0
		.amdhsa_system_sgpr_workgroup_id_x 1
		.amdhsa_system_sgpr_workgroup_id_y 0
		.amdhsa_system_sgpr_workgroup_id_z 0
		.amdhsa_system_sgpr_workgroup_info 0
		.amdhsa_system_vgpr_workitem_id 0
		.amdhsa_next_free_vgpr 256
		.amdhsa_next_free_sgpr 102
		.amdhsa_accum_offset 256
		.amdhsa_reserve_vcc 1
		.amdhsa_float_round_mode_32 0
		.amdhsa_float_round_mode_16_64 0
		.amdhsa_float_denorm_mode_32 3
		.amdhsa_float_denorm_mode_16_64 3
		.amdhsa_dx10_clamp 1
		.amdhsa_ieee_mode 1
		.amdhsa_fp16_overflow 0
		.amdhsa_tg_split 0
		.amdhsa_exception_fp_ieee_invalid_op 0
		.amdhsa_exception_fp_denorm_src 0
		.amdhsa_exception_fp_ieee_div_zero 0
		.amdhsa_exception_fp_ieee_overflow 0
		.amdhsa_exception_fp_ieee_underflow 0
		.amdhsa_exception_fp_ieee_inexact 0
		.amdhsa_exception_int_div_zero 0
	.end_amdhsa_kernel

amdhsa.kernels:
  - .agpr_count:     0
    .args:
      - .offset:         0
        .size:           240
        .value_kind:     by_value
      - .offset:         240
        .size:           4
        .value_kind:     hidden_block_count_x
      - .offset:         244
        .size:           4
        .value_kind:     hidden_block_count_y
      - .offset:         248
        .size:           4
        .value_kind:     hidden_block_count_z
      - .offset:         252
        .size:           2
        .value_kind:     hidden_group_size_x
      - .offset:         254
        .size:           2
        .value_kind:     hidden_group_size_y
      - .offset:         256
        .size:           2
        .value_kind:     hidden_group_size_z
      - .offset:         258
        .size:           2
        .value_kind:     hidden_remainder_x
      - .offset:         260
        .size:           2
        .value_kind:     hidden_remainder_y
      - .offset:         262
        .size:           2
        .value_kind:     hidden_remainder_z
      - .offset:         280
        .size:           8
        .value_kind:     hidden_global_offset_x
      - .offset:         288
        .size:           8
        .value_kind:     hidden_global_offset_y
      - .offset:         296
        .size:           8
        .value_kind:     hidden_global_offset_z
      - .offset:         304
        .size:           2
        .value_kind:     hidden_grid_dims
      - .offset:         360
        .size:           4
        .value_kind:     hidden_dynamic_lds_size
    .group_segment_fixed_size: 0
    .kernarg_segment_align: 8
    .kernarg_segment_size: 496
    .language:       OpenCL C
    .language_version:
      - 2
      - 0
    .max_flat_workgroup_size: 512
    .name:           _Z9trunk_fwd4Args
    .private_segment_fixed_size: 0
    .sgpr_count:     108
    .sgpr_spill_count: 289
    .symbol:         _Z9trunk_fwd4Args.kd
    .uniform_work_group_size: 1
    .uses_dynamic_stack: false
    .vgpr_count:     256
    .vgpr_spill_count: 0
    .wavefront_size: 64
